# mixer A: staging ladder waits only for the staging loads (exact vmcnt 24..13) on top of the q-fragment wait fix
# baseline (speedup 1.0000x reference)
; #define A_STORE() do { _Pragma("unroll") for (int it = 0; it < 6; ++it) { *(LAS u32x4*)(kt_l + (it * 64 + srow) * AST + sch * 16) = kst[it]; *(LAS u32x4*)(vt_l + (it * 64 + srow) * AST + sch * 16) = vst[it]; } } while (0)
; __device__ __forceinline__ void attnA_unit(LAS unsigned char* lds, const Args& A, int unit) {
;     ...
;             if (sb + 1 < nsb) { A_STORE(); __syncthreads(); }
.LBB0_304:
	s_or_b64 exec, exec, s[46:47]
	s_andn2_b64 vcc, exec, s[82:83]
	s_barrier
	s_cbranch_vccnz .LBB0_306
	s_cmp_eq_u64 s[78:79], 0
	s_cbranch_scc1 .LmixA_st_idle
	s_waitcnt vmcnt(24)
	ds_write_b128 v207, v[96:99] offset:4096
	s_waitcnt vmcnt(23)
	ds_write_b128 v207, v[100:103] offset:59392
	s_waitcnt vmcnt(22)
	ds_write_b128 v207, v[104:107] offset:13312
	s_waitcnt vmcnt(21)
	ds_write_b128 v201, v[108:111] offset:59392
	s_waitcnt vmcnt(20)
	ds_write_b128 v207, v[112:115] offset:22528
	s_waitcnt vmcnt(19)
	ds_write_b128 v202, v[116:119] offset:59392
	s_waitcnt vmcnt(18)
	ds_write_b128 v207, v[120:123] offset:31744
	s_waitcnt vmcnt(17)
	ds_write_b128 v203, v[124:127] offset:59392
	s_waitcnt vmcnt(16)
	ds_write_b128 v207, v[128:131] offset:40960
	s_waitcnt vmcnt(15)
	ds_write_b128 v204, v[132:135] offset:59392
	s_waitcnt vmcnt(14)
	ds_write_b128 v207, v[136:139] offset:50176
	s_waitcnt vmcnt(13)
	ds_write_b128 v205, v[140:143] offset:59392
	s_branch .LmixA_st_done
.LmixA_st_idle:
	s_waitcnt vmcnt(11)
	ds_write_b128 v207, v[96:99] offset:4096
	s_waitcnt vmcnt(10)
	ds_write_b128 v207, v[100:103] offset:59392
	s_waitcnt vmcnt(9)
	ds_write_b128 v207, v[104:107] offset:13312
	s_waitcnt vmcnt(8)
	ds_write_b128 v201, v[108:111] offset:59392
	s_waitcnt vmcnt(7)
	ds_write_b128 v207, v[112:115] offset:22528
	s_waitcnt vmcnt(6)
	ds_write_b128 v202, v[116:119] offset:59392
	s_waitcnt vmcnt(5)
	ds_write_b128 v207, v[120:123] offset:31744
	s_waitcnt vmcnt(4)
	ds_write_b128 v203, v[124:127] offset:59392
	s_waitcnt vmcnt(3)
	ds_write_b128 v207, v[128:131] offset:40960
	s_waitcnt vmcnt(2)
	ds_write_b128 v204, v[132:135] offset:59392
	s_waitcnt vmcnt(1)
	ds_write_b128 v207, v[136:139] offset:50176
	s_waitcnt vmcnt(0)
	ds_write_b128 v205, v[140:143] offset:59392
.LmixA_st_done:
	s_waitcnt lgkmcnt(0)
	s_barrier
